# in-proj q/k epilogue: rope-table loads of each row group issued before the head-norm reduction (into free k-loop fragment registers) instead of right before use
# speedup vs baseline: 1.0264x; 1.0024x over previous
.LBB0_929:
	s_andn2_b64 vcc, exec, s[0:1]
	v_lshl_add_u64 v[28:29], s[14:15], 0, v[10:11]
	s_cbranch_vccnz .LBB0_942
	v_cmp_lt_i32_e64 s[0:1], s43, v42
	v_cmp_gt_i32_e32 vcc, s80, v42
	s_and_saveexec_b64 s[4:5], vcc
	s_xor_b64 s[4:5], exec, s[4:5]
	v_and_b32_e32 v10, 0xff, v42
	s_or_saveexec_b64 s[4:5], s[4:5]
	v_mov_b32_e32 v44, v42
	s_xor_b64 exec, exec, s[4:5]
	v_add_u32_e32 v10, 0xffffe000, v42
	v_lshrrev_b32_e32 v11, 12, v10
	v_and_b32_e32 v10, 0xfff, v42
	v_mul_u32_u24_e32 v11, 0x1200, v11
	s_movk_i32 s34, 0x2200
	v_add3_u32 v44, v10, v11, s34
	s_or_b64 exec, exec, s[4:5]
	v_lshrrev_b32_e32 v196, 6, v10
	v_and_b32_e32 v197, 63, v10
	v_cndmask_b32_e64 v197, v197, v196, s[38:39]
	v_lshlrev_b32_e32 v196, 2, v115
	v_lshl_or_b32 v198, v197, 6, v196
	global_load_dwordx4 v[180:183], v198, s[10:11] offset:16
	global_load_dwordx4 v[184:187], v198, s[10:11]
	global_load_dwordx4 v[188:191], v198, s[12:13] offset:16
	global_load_dwordx4 v[192:195], v198, s[12:13]
	s_waitcnt lgkmcnt(1)
	v_pk_mul_f32 v[14:15], v[2:3], v[2:3]
	v_pk_mul_f32 v[12:13], v[4:5], v[4:5]
	v_add_f32_e32 v11, v14, v15
	v_add_f32_e32 v11, v12, v11
	s_waitcnt lgkmcnt(0)
	v_pk_mul_f32 v[18:19], v[6:7], v[6:7]
	v_add_f32_e32 v11, v13, v11
	v_add_f32_e32 v11, v18, v11
	v_pk_mul_f32 v[16:17], v[8:9], v[8:9]
	v_add_f32_e32 v11, v19, v11
	v_cmp_lt_i32_e32 vcc, v214, v215
	v_add_f32_e32 v11, v16, v11
	v_add_f32_e32 v11, v17, v11
	v_cndmask_b32_e32 v12, v213, v214, vcc
	v_lshlrev_b32_e32 v12, 2, v12
	ds_bpermute_b32 v12, v12, v11
	v_cmp_lt_i32_e32 vcc, v216, v215
	s_nor_b64 s[34:35], s[20:21], s[0:1]
	v_ashrrev_i32_e32 v43, 31, v42
	s_waitcnt lgkmcnt(0)
	v_add_f32_e32 v11, v11, v12
	v_cndmask_b32_e32 v12, v213, v216, vcc
	v_lshlrev_b32_e32 v12, 2, v12
	ds_bpermute_b32 v12, v12, v11
	v_cmp_lt_i32_e32 vcc, v217, v215
	s_waitcnt lgkmcnt(0)
	v_add_f32_e32 v11, v11, v12
	v_cndmask_b32_e32 v12, v213, v217, vcc
	v_lshlrev_b32_e32 v12, 2, v12
	ds_bpermute_b32 v12, v12, v11
	s_waitcnt lgkmcnt(0)
	v_add_f32_e32 v11, v11, v12
	v_fmamk_f32 v11, v11, 0x3c800000, v207
	v_mul_f32_e32 v12, 0x4b800000, v11
	v_cmp_gt_f32_e32 vcc, s42, v11
	s_nop 1
	v_cndmask_b32_e32 v11, v11, v12, vcc
	v_rsq_f32_e32 v11, v11
	s_nop 0
	v_mul_f32_e32 v12, 0x45800000, v11
	v_cndmask_b32_e32 v46, v11, v12, vcc
	v_pk_mul_f32 v[2:3], v[2:3], v[46:47] op_sel_hi:[1,0]
	v_pk_mul_f32 v[4:5], v[4:5], v[46:47] op_sel_hi:[1,0]
	v_pk_mul_f32 v[6:7], v[6:7], v[46:47] op_sel_hi:[1,0]
	v_pk_mul_f32 v[8:9], v[8:9], v[46:47] op_sel_hi:[1,0]
	s_waitcnt vmcnt(4)
	v_pk_mul_f32 v[2:3], v[32:33], v[2:3]
	v_pk_mul_f32 v[4:5], v[34:35], v[4:5]
	v_pk_mul_f32 v[6:7], v[36:37], v[6:7]
	v_pk_mul_f32 v[8:9], v[38:39], v[8:9]
	s_and_saveexec_b64 s[4:5], s[34:35]
	s_cbranch_execz .LBB0_936
	v_readlane_b32 s34, v254, 13
	v_lshlrev_b64 v[12:13], 9, v[42:43]
	v_readlane_b32 s35, v254, 14
	s_nop 1
	v_lshl_add_u64 v[12:13], s[34:35], 0, v[12:13]
	v_lshl_add_u64 v[12:13], v[40:41], 2, v[12:13]
	v_add_co_u32_e32 v12, vcc, 0x5fff000, v12
	s_nop 1
	v_addc_co_u32_e32 v13, vcc, 0, v13, vcc
	global_store_dwordx4 v[12:13], v[2:5], off offset:2048
	global_store_dwordx4 v[12:13], v[6:9], off offset:2064
.LBB0_936:
	s_or_b64 exec, exec, s[4:5]
	s_and_saveexec_b64 s[4:5], s[0:1]
	s_cbranch_execz .LBB0_938
	ds_read_b128 v[50:53], v118
	ds_read_b128 v[54:57], v118 offset:16
	v_lshrrev_b32_e32 v11, 6, v10
	v_and_b32_e32 v10, 63, v10
	v_mov_b32_e32 v47, v46
	v_cndmask_b32_e64 v10, v10, v11, s[38:39]
	v_lshlrev_b32_e32 v11, 2, v115
	v_lshl_or_b32 v45, v10, 6, v11
	s_waitcnt lgkmcnt(1)
	v_pk_mul_f32 v[10:11], v[46:47], v[50:51]
	v_pk_mul_f32 v[52:53], v[46:47], v[52:53]
	v_pk_mul_f32 v[50:51], v[24:25], v[10:11]
	s_waitcnt vmcnt(0)
	v_mov_b64_e32 v[10:11], v[180:181]
	v_mov_b64_e32 v[12:13], v[182:183]
	v_mov_b64_e32 v[14:15], v[184:185]
	v_mov_b64_e32 v[16:17], v[186:187]
	v_mov_b64_e32 v[18:19], v[188:189]
	v_mov_b64_e32 v[20:21], v[190:191]
	v_mov_b64_e32 v[58:59], v[192:193]
	v_mov_b64_e32 v[60:61], v[194:195]
	s_waitcnt lgkmcnt(0)
	v_mul_f32_e32 v45, v46, v56
	v_mul_f32_e32 v45, v0, v45
	v_pk_mul_f32 v[54:55], v[46:47], v[54:55]
	v_pk_mul_f32 v[52:53], v[26:27], v[52:53]
	v_pk_mul_f32 v[54:55], v[30:31], v[54:55]
	v_cndmask_b32_e64 v51, v51, -v51, s[40:41]
	v_cndmask_b32_e64 v50, v50, -v50, s[40:41]
	v_cndmask_b32_e64 v53, v53, -v53, s[40:41]
	v_cndmask_b32_e64 v52, v52, -v52, s[40:41]
	v_cndmask_b32_e64 v55, v55, -v55, s[40:41]
	v_cndmask_b32_e64 v54, v54, -v54, s[40:41]
	s_waitcnt vmcnt(3)
	v_mul_f32_e32 v8, v8, v12
	v_cndmask_b32_e64 v12, v45, -v45, s[40:41]
	s_waitcnt vmcnt(1)
	v_mul_f32_e32 v12, v12, v20
	v_mul_f32_e32 v20, v46, v57
	v_mul_f32_e32 v20, v48, v20
	v_cndmask_b32_e64 v47, v20, -v20, s[40:41]
	v_mov_b32_e32 v46, v9
	v_mov_b32_e32 v20, v13
	v_pk_mul_f32 v[20:21], v[46:47], v[20:21]
	s_waitcnt vmcnt(0)
	v_pk_mul_f32 v[50:51], v[58:59], v[50:51]
	v_pk_mul_f32 v[52:53], v[52:53], v[60:61]
	v_pk_mul_f32 v[18:19], v[54:55], v[18:19]
	v_mov_b32_e32 v9, v20
	v_mov_b32_e32 v13, v21
	v_pk_fma_f32 v[2:3], v[2:3], v[14:15], v[50:51]
	v_pk_fma_f32 v[4:5], v[4:5], v[16:17], v[52:53]
	v_pk_fma_f32 v[6:7], v[6:7], v[10:11], v[18:19]
	v_pk_add_f32 v[8:9], v[8:9], v[12:13]

.LBB0_952:
	s_andn2_b64 vcc, exec, s[0:1]
	s_cbranch_vccnz .LBB0_965
	v_cmp_lt_i32_e64 s[0:1], s43, v42
	v_cmp_gt_i32_e32 vcc, s80, v42
	s_and_saveexec_b64 s[24:25], vcc
	s_xor_b64 s[24:25], exec, s[24:25]
	v_and_b32_e32 v10, 0xff, v42
	s_or_saveexec_b64 s[24:25], s[24:25]
	v_mov_b32_e32 v44, v42
	s_xor_b64 exec, exec, s[24:25]
	v_add_u32_e32 v10, 0xffffe000, v42
	v_lshrrev_b32_e32 v11, 12, v10
	v_and_b32_e32 v10, 0xfff, v42
	v_mul_u32_u24_e32 v11, 0x1200, v11
	s_movk_i32 s34, 0x2200
	v_add3_u32 v44, v10, v11, s34
	s_or_b64 exec, exec, s[24:25]
	v_lshrrev_b32_e32 v196, 6, v10
	v_and_b32_e32 v197, 63, v10
	v_cndmask_b32_e64 v197, v197, v196, s[38:39]
	v_lshlrev_b32_e32 v196, 2, v115
	v_lshl_or_b32 v198, v197, 6, v196
	global_load_dwordx4 v[180:183], v198, s[10:11] offset:16
	global_load_dwordx4 v[184:187], v198, s[10:11]
	global_load_dwordx4 v[188:191], v198, s[12:13] offset:16
	global_load_dwordx4 v[192:195], v198, s[12:13]
	s_waitcnt lgkmcnt(1)
	v_pk_mul_f32 v[14:15], v[2:3], v[2:3]
	v_pk_mul_f32 v[12:13], v[4:5], v[4:5]
	v_add_f32_e32 v11, v14, v15
	v_add_f32_e32 v11, v12, v11
	s_waitcnt lgkmcnt(0)
	v_pk_mul_f32 v[18:19], v[6:7], v[6:7]
	v_add_f32_e32 v11, v13, v11
	v_add_f32_e32 v11, v18, v11
	v_pk_mul_f32 v[16:17], v[8:9], v[8:9]
	v_add_f32_e32 v11, v19, v11
	v_cmp_lt_i32_e32 vcc, v214, v215
	v_add_f32_e32 v11, v16, v11
	v_add_f32_e32 v11, v17, v11
	v_cndmask_b32_e32 v12, v213, v214, vcc
	v_lshlrev_b32_e32 v12, 2, v12
	ds_bpermute_b32 v12, v12, v11
	v_cmp_lt_i32_e32 vcc, v216, v215
	s_nor_b64 s[34:35], s[20:21], s[0:1]
	v_ashrrev_i32_e32 v43, 31, v42
	s_waitcnt lgkmcnt(0)
	v_add_f32_e32 v11, v11, v12
	v_cndmask_b32_e32 v12, v213, v216, vcc
	v_lshlrev_b32_e32 v12, 2, v12
	ds_bpermute_b32 v12, v12, v11
	v_cmp_lt_i32_e32 vcc, v217, v215
	s_waitcnt lgkmcnt(0)
	v_add_f32_e32 v11, v11, v12
	v_cndmask_b32_e32 v12, v213, v217, vcc
	v_lshlrev_b32_e32 v12, 2, v12
	ds_bpermute_b32 v12, v12, v11
	s_waitcnt lgkmcnt(0)
	v_add_f32_e32 v11, v11, v12
	v_fmamk_f32 v11, v11, 0x3c800000, v207
	v_mul_f32_e32 v12, 0x4b800000, v11
	v_cmp_gt_f32_e32 vcc, s42, v11
	s_nop 1
	v_cndmask_b32_e32 v11, v11, v12, vcc
	v_rsq_f32_e32 v11, v11
	s_nop 0
	v_mul_f32_e32 v12, 0x45800000, v11
	v_cndmask_b32_e32 v46, v11, v12, vcc
	v_pk_mul_f32 v[2:3], v[2:3], v[46:47] op_sel_hi:[1,0]
	v_pk_mul_f32 v[4:5], v[4:5], v[46:47] op_sel_hi:[1,0]
	v_pk_mul_f32 v[6:7], v[6:7], v[46:47] op_sel_hi:[1,0]
	v_pk_mul_f32 v[8:9], v[8:9], v[46:47] op_sel_hi:[1,0]
	s_waitcnt vmcnt(4)
	v_pk_mul_f32 v[2:3], v[32:33], v[2:3]
	v_pk_mul_f32 v[4:5], v[34:35], v[4:5]
	v_pk_mul_f32 v[6:7], v[36:37], v[6:7]
	v_pk_mul_f32 v[8:9], v[38:39], v[8:9]
	s_and_saveexec_b64 s[24:25], s[34:35]
	s_cbranch_execz .LBB0_959
	v_readlane_b32 s34, v254, 13
	v_lshlrev_b64 v[12:13], 9, v[42:43]
	v_readlane_b32 s35, v254, 14
	s_nop 1
	v_lshl_add_u64 v[12:13], s[34:35], 0, v[12:13]
	v_lshl_add_u64 v[12:13], v[40:41], 2, v[12:13]
	v_add_co_u32_e32 v12, vcc, 0x5fff000, v12
	s_nop 1
	v_addc_co_u32_e32 v13, vcc, 0, v13, vcc
	global_store_dwordx4 v[12:13], v[2:5], off offset:2048
	global_store_dwordx4 v[12:13], v[6:9], off offset:2064
.LBB0_959:
	s_or_b64 exec, exec, s[24:25]
	s_and_saveexec_b64 s[24:25], s[0:1]
	s_cbranch_execz .LBB0_961
	ds_read_b128 v[50:53], v121
	ds_read_b128 v[54:57], v121 offset:16
	v_lshrrev_b32_e32 v11, 6, v10
	v_and_b32_e32 v10, 63, v10
	v_mov_b32_e32 v47, v46
	v_cndmask_b32_e64 v10, v10, v11, s[38:39]
	v_lshlrev_b32_e32 v11, 2, v115
	v_lshl_or_b32 v45, v10, 6, v11
	s_waitcnt lgkmcnt(1)
	v_pk_mul_f32 v[10:11], v[46:47], v[50:51]
	v_pk_mul_f32 v[52:53], v[46:47], v[52:53]
	v_pk_mul_f32 v[50:51], v[24:25], v[10:11]
	s_waitcnt vmcnt(0)
	v_mov_b64_e32 v[10:11], v[180:181]
	v_mov_b64_e32 v[12:13], v[182:183]
	v_mov_b64_e32 v[14:15], v[184:185]
	v_mov_b64_e32 v[16:17], v[186:187]
	v_mov_b64_e32 v[18:19], v[188:189]
	v_mov_b64_e32 v[20:21], v[190:191]
	v_mov_b64_e32 v[58:59], v[192:193]
	v_mov_b64_e32 v[60:61], v[194:195]
	s_waitcnt lgkmcnt(0)
	v_mul_f32_e32 v45, v46, v56
	v_mul_f32_e32 v45, v0, v45
	v_pk_mul_f32 v[54:55], v[46:47], v[54:55]
	v_pk_mul_f32 v[52:53], v[26:27], v[52:53]
	v_pk_mul_f32 v[54:55], v[30:31], v[54:55]
	v_cndmask_b32_e64 v51, v51, -v51, s[40:41]
	v_cndmask_b32_e64 v50, v50, -v50, s[40:41]
	v_cndmask_b32_e64 v53, v53, -v53, s[40:41]
	v_cndmask_b32_e64 v52, v52, -v52, s[40:41]
	v_cndmask_b32_e64 v55, v55, -v55, s[40:41]
	v_cndmask_b32_e64 v54, v54, -v54, s[40:41]
	s_waitcnt vmcnt(3)
	v_mul_f32_e32 v8, v8, v12
	v_cndmask_b32_e64 v12, v45, -v45, s[40:41]
	s_waitcnt vmcnt(1)
	v_mul_f32_e32 v12, v12, v20
	v_mul_f32_e32 v20, v46, v57
	v_mul_f32_e32 v20, v48, v20
	v_cndmask_b32_e64 v47, v20, -v20, s[40:41]
	v_mov_b32_e32 v46, v9
	v_mov_b32_e32 v20, v13
	v_pk_mul_f32 v[20:21], v[46:47], v[20:21]
	s_waitcnt vmcnt(0)
	v_pk_mul_f32 v[50:51], v[58:59], v[50:51]
	v_pk_mul_f32 v[52:53], v[52:53], v[60:61]
	v_pk_mul_f32 v[18:19], v[54:55], v[18:19]
	v_mov_b32_e32 v9, v20
	v_mov_b32_e32 v13, v21
	v_pk_fma_f32 v[2:3], v[2:3], v[14:15], v[50:51]
	v_pk_fma_f32 v[4:5], v[4:5], v[16:17], v[52:53]
	v_pk_fma_f32 v[6:7], v[6:7], v[10:11], v[18:19]
	v_pk_add_f32 v[8:9], v[8:9], v[12:13]

.LBB0_982:
	s_or_b64 exec, exec, s[24:25]
	s_and_saveexec_b64 s[24:25], s[0:1]
	s_cbranch_execz .LBB0_984
	ds_read_b128 v[50:53], v124
	ds_read_b128 v[54:57], v124 offset:16
	v_lshrrev_b32_e32 v11, 6, v10
	v_and_b32_e32 v10, 63, v10
	v_mov_b32_e32 v47, v46
	v_cndmask_b32_e64 v10, v10, v11, s[38:39]
	v_lshlrev_b32_e32 v11, 2, v115
	v_lshl_or_b32 v45, v10, 6, v11
	s_waitcnt lgkmcnt(1)
	v_pk_mul_f32 v[10:11], v[46:47], v[50:51]
	v_pk_mul_f32 v[52:53], v[46:47], v[52:53]
	v_pk_mul_f32 v[50:51], v[24:25], v[10:11]
	s_waitcnt vmcnt(0)
	v_mov_b64_e32 v[10:11], v[180:181]
	v_mov_b64_e32 v[12:13], v[182:183]
	v_mov_b64_e32 v[14:15], v[184:185]
	v_mov_b64_e32 v[16:17], v[186:187]
	v_mov_b64_e32 v[18:19], v[188:189]
	v_mov_b64_e32 v[20:21], v[190:191]
	v_mov_b64_e32 v[58:59], v[192:193]
	v_mov_b64_e32 v[60:61], v[194:195]
	s_waitcnt lgkmcnt(0)
	v_mul_f32_e32 v45, v46, v56
	v_mul_f32_e32 v45, v0, v45
	v_pk_mul_f32 v[54:55], v[46:47], v[54:55]
	v_pk_mul_f32 v[52:53], v[26:27], v[52:53]
	v_pk_mul_f32 v[54:55], v[30:31], v[54:55]
	v_cndmask_b32_e64 v51, v51, -v51, s[40:41]
	v_cndmask_b32_e64 v50, v50, -v50, s[40:41]
	v_cndmask_b32_e64 v53, v53, -v53, s[40:41]
	v_cndmask_b32_e64 v52, v52, -v52, s[40:41]
	v_cndmask_b32_e64 v55, v55, -v55, s[40:41]
	v_cndmask_b32_e64 v54, v54, -v54, s[40:41]
	s_waitcnt vmcnt(3)
	v_mul_f32_e32 v8, v8, v12
	v_cndmask_b32_e64 v12, v45, -v45, s[40:41]
	s_waitcnt vmcnt(1)
	v_mul_f32_e32 v12, v12, v20
	v_mul_f32_e32 v20, v46, v57
	v_mul_f32_e32 v20, v48, v20
	v_cndmask_b32_e64 v47, v20, -v20, s[40:41]
	v_mov_b32_e32 v46, v9
	v_mov_b32_e32 v20, v13
	v_pk_mul_f32 v[20:21], v[46:47], v[20:21]
	s_waitcnt vmcnt(0)
	v_pk_mul_f32 v[50:51], v[58:59], v[50:51]
	v_pk_mul_f32 v[52:53], v[52:53], v[60:61]
	v_pk_mul_f32 v[18:19], v[54:55], v[18:19]
	v_mov_b32_e32 v9, v20
	v_mov_b32_e32 v13, v21
	v_pk_fma_f32 v[2:3], v[2:3], v[14:15], v[50:51]
	v_pk_fma_f32 v[4:5], v[4:5], v[16:17], v[52:53]
	v_pk_fma_f32 v[6:7], v[6:7], v[10:11], v[18:19]
	v_pk_add_f32 v[8:9], v[8:9], v[12:13]

.LBB0_1005:
	s_or_b64 exec, exec, s[24:25]
	s_and_saveexec_b64 s[24:25], s[0:1]
	s_cbranch_execz .LBB0_1007
	ds_read_b128 v[50:53], v127
	ds_read_b128 v[54:57], v127 offset:16
	v_lshrrev_b32_e32 v11, 6, v10
	v_and_b32_e32 v10, 63, v10
	v_mov_b32_e32 v47, v46
	v_cndmask_b32_e64 v10, v10, v11, s[38:39]
	v_lshlrev_b32_e32 v11, 2, v115
	v_lshl_or_b32 v45, v10, 6, v11
	s_waitcnt lgkmcnt(1)
	v_pk_mul_f32 v[10:11], v[46:47], v[50:51]
	v_pk_mul_f32 v[52:53], v[46:47], v[52:53]
	v_pk_mul_f32 v[50:51], v[24:25], v[10:11]
	s_waitcnt vmcnt(0)
	v_mov_b64_e32 v[10:11], v[180:181]
	v_mov_b64_e32 v[12:13], v[182:183]
	v_mov_b64_e32 v[14:15], v[184:185]
	v_mov_b64_e32 v[16:17], v[186:187]
	v_mov_b64_e32 v[18:19], v[188:189]
	v_mov_b64_e32 v[20:21], v[190:191]
	v_mov_b64_e32 v[58:59], v[192:193]
	v_mov_b64_e32 v[60:61], v[194:195]
	s_waitcnt lgkmcnt(0)
	v_mul_f32_e32 v45, v46, v56
	v_mul_f32_e32 v45, v0, v45
	v_pk_mul_f32 v[54:55], v[46:47], v[54:55]
	v_pk_mul_f32 v[52:53], v[26:27], v[52:53]
	v_pk_mul_f32 v[54:55], v[30:31], v[54:55]
	v_cndmask_b32_e64 v51, v51, -v51, s[40:41]
	v_cndmask_b32_e64 v50, v50, -v50, s[40:41]
	v_cndmask_b32_e64 v53, v53, -v53, s[40:41]
	v_cndmask_b32_e64 v52, v52, -v52, s[40:41]
	v_cndmask_b32_e64 v55, v55, -v55, s[40:41]
	v_cndmask_b32_e64 v54, v54, -v54, s[40:41]
	s_waitcnt vmcnt(3)
	v_mul_f32_e32 v8, v8, v12
	v_cndmask_b32_e64 v12, v45, -v45, s[40:41]
	s_waitcnt vmcnt(1)
	v_mul_f32_e32 v12, v12, v20
	v_mul_f32_e32 v20, v46, v57
	v_mul_f32_e32 v20, v48, v20
	v_cndmask_b32_e64 v47, v20, -v20, s[40:41]
	v_mov_b32_e32 v46, v9
	v_mov_b32_e32 v20, v13
	v_pk_mul_f32 v[20:21], v[46:47], v[20:21]
	s_waitcnt vmcnt(0)
	v_pk_mul_f32 v[50:51], v[58:59], v[50:51]
	v_pk_mul_f32 v[52:53], v[52:53], v[60:61]
	v_pk_mul_f32 v[18:19], v[54:55], v[18:19]
	v_mov_b32_e32 v9, v20
	v_mov_b32_e32 v13, v21
	v_pk_fma_f32 v[2:3], v[2:3], v[14:15], v[50:51]
	v_pk_fma_f32 v[4:5], v[4:5], v[16:17], v[52:53]
	v_pk_fma_f32 v[6:7], v[6:7], v[10:11], v[18:19]
	v_pk_add_f32 v[8:9], v[8:9], v[12:13]

.LBB0_1028:
	s_or_b64 exec, exec, s[24:25]
	s_and_saveexec_b64 s[24:25], s[0:1]
	s_cbranch_execz .LBB0_1030
	ds_read_b128 v[50:53], v130
	ds_read_b128 v[54:57], v130 offset:16
	v_lshrrev_b32_e32 v11, 6, v10
	v_and_b32_e32 v10, 63, v10
	v_mov_b32_e32 v47, v46
	v_cndmask_b32_e64 v10, v10, v11, s[38:39]
	v_lshlrev_b32_e32 v11, 2, v115
	v_lshl_or_b32 v45, v10, 6, v11
	s_waitcnt lgkmcnt(1)
	v_pk_mul_f32 v[10:11], v[46:47], v[50:51]
	v_pk_mul_f32 v[52:53], v[46:47], v[52:53]
	v_pk_mul_f32 v[50:51], v[24:25], v[10:11]
	s_waitcnt vmcnt(0)
	v_mov_b64_e32 v[10:11], v[180:181]
	v_mov_b64_e32 v[12:13], v[182:183]
	v_mov_b64_e32 v[14:15], v[184:185]
	v_mov_b64_e32 v[16:17], v[186:187]
	v_mov_b64_e32 v[18:19], v[188:189]
	v_mov_b64_e32 v[20:21], v[190:191]
	v_mov_b64_e32 v[58:59], v[192:193]
	v_mov_b64_e32 v[60:61], v[194:195]
	s_waitcnt lgkmcnt(0)
	v_mul_f32_e32 v45, v46, v56
	v_mul_f32_e32 v45, v0, v45
	v_pk_mul_f32 v[54:55], v[46:47], v[54:55]
	v_pk_mul_f32 v[52:53], v[26:27], v[52:53]
	v_pk_mul_f32 v[54:55], v[30:31], v[54:55]
	v_cndmask_b32_e64 v51, v51, -v51, s[40:41]
	v_cndmask_b32_e64 v50, v50, -v50, s[40:41]
	v_cndmask_b32_e64 v53, v53, -v53, s[40:41]
	v_cndmask_b32_e64 v52, v52, -v52, s[40:41]
	v_cndmask_b32_e64 v55, v55, -v55, s[40:41]
	v_cndmask_b32_e64 v54, v54, -v54, s[40:41]
	s_waitcnt vmcnt(3)
	v_mul_f32_e32 v8, v8, v12
	v_cndmask_b32_e64 v12, v45, -v45, s[40:41]
	s_waitcnt vmcnt(1)
	v_mul_f32_e32 v12, v12, v20
	v_mul_f32_e32 v20, v46, v57
	v_mul_f32_e32 v20, v48, v20
	v_cndmask_b32_e64 v47, v20, -v20, s[40:41]
	v_mov_b32_e32 v46, v9
	v_mov_b32_e32 v20, v13
	v_pk_mul_f32 v[20:21], v[46:47], v[20:21]
	s_waitcnt vmcnt(0)
	v_pk_mul_f32 v[50:51], v[58:59], v[50:51]
	v_pk_mul_f32 v[52:53], v[52:53], v[60:61]
	v_pk_mul_f32 v[18:19], v[54:55], v[18:19]
	v_mov_b32_e32 v9, v20
	v_mov_b32_e32 v13, v21
	v_pk_fma_f32 v[2:3], v[2:3], v[14:15], v[50:51]
	v_pk_fma_f32 v[4:5], v[4:5], v[16:17], v[52:53]
	v_pk_fma_f32 v[6:7], v[6:7], v[10:11], v[18:19]
	v_pk_add_f32 v[8:9], v[8:9], v[12:13]

.LBB0_1051:
	s_or_b64 exec, exec, s[24:25]
	s_and_saveexec_b64 s[24:25], s[0:1]
	s_cbranch_execz .LBB0_1053
	ds_read_b128 v[50:53], v133
	ds_read_b128 v[54:57], v133 offset:16
	v_lshrrev_b32_e32 v11, 6, v10
	v_and_b32_e32 v10, 63, v10
	v_mov_b32_e32 v47, v46
	v_cndmask_b32_e64 v10, v10, v11, s[38:39]
	v_lshlrev_b32_e32 v11, 2, v115
	v_lshl_or_b32 v45, v10, 6, v11
	s_waitcnt lgkmcnt(1)
	v_pk_mul_f32 v[10:11], v[46:47], v[50:51]
	v_pk_mul_f32 v[52:53], v[46:47], v[52:53]
	v_pk_mul_f32 v[50:51], v[24:25], v[10:11]
	s_waitcnt vmcnt(0)
	v_mov_b64_e32 v[10:11], v[180:181]
	v_mov_b64_e32 v[12:13], v[182:183]
	v_mov_b64_e32 v[14:15], v[184:185]
	v_mov_b64_e32 v[16:17], v[186:187]
	v_mov_b64_e32 v[18:19], v[188:189]
	v_mov_b64_e32 v[20:21], v[190:191]
	v_mov_b64_e32 v[58:59], v[192:193]
	v_mov_b64_e32 v[60:61], v[194:195]
	s_waitcnt lgkmcnt(0)
	v_mul_f32_e32 v45, v46, v56
	v_mul_f32_e32 v45, v0, v45
	v_pk_mul_f32 v[54:55], v[46:47], v[54:55]
	v_pk_mul_f32 v[52:53], v[26:27], v[52:53]
	v_pk_mul_f32 v[54:55], v[30:31], v[54:55]
	v_cndmask_b32_e64 v51, v51, -v51, s[40:41]
	v_cndmask_b32_e64 v50, v50, -v50, s[40:41]
	v_cndmask_b32_e64 v53, v53, -v53, s[40:41]
	v_cndmask_b32_e64 v52, v52, -v52, s[40:41]
	v_cndmask_b32_e64 v55, v55, -v55, s[40:41]
	v_cndmask_b32_e64 v54, v54, -v54, s[40:41]
	s_waitcnt vmcnt(3)
	v_mul_f32_e32 v8, v8, v12
	v_cndmask_b32_e64 v12, v45, -v45, s[40:41]
	s_waitcnt vmcnt(1)
	v_mul_f32_e32 v12, v12, v20
	v_mul_f32_e32 v20, v46, v57
	v_mul_f32_e32 v20, v48, v20
	v_cndmask_b32_e64 v47, v20, -v20, s[40:41]
	v_mov_b32_e32 v46, v9
	v_mov_b32_e32 v20, v13
	v_pk_mul_f32 v[20:21], v[46:47], v[20:21]
	s_waitcnt vmcnt(0)
	v_pk_mul_f32 v[50:51], v[58:59], v[50:51]
	v_pk_mul_f32 v[52:53], v[52:53], v[60:61]
	v_pk_mul_f32 v[18:19], v[54:55], v[18:19]
	v_mov_b32_e32 v9, v20
	v_mov_b32_e32 v13, v21
	v_pk_fma_f32 v[2:3], v[2:3], v[14:15], v[50:51]
	v_pk_fma_f32 v[4:5], v[4:5], v[16:17], v[52:53]
	v_pk_fma_f32 v[6:7], v[6:7], v[10:11], v[18:19]
	v_pk_add_f32 v[8:9], v[8:9], v[12:13]

.LBB0_1074:
	s_or_b64 exec, exec, s[24:25]
	s_and_saveexec_b64 s[24:25], s[0:1]
	s_cbranch_execz .LBB0_1076
	ds_read_b128 v[50:53], v136
	ds_read_b128 v[54:57], v136 offset:16
	v_lshrrev_b32_e32 v11, 6, v10
	v_and_b32_e32 v10, 63, v10
	v_mov_b32_e32 v47, v46
	v_cndmask_b32_e64 v10, v10, v11, s[38:39]
	v_lshlrev_b32_e32 v11, 2, v115
	v_lshl_or_b32 v45, v10, 6, v11
	s_waitcnt lgkmcnt(1)
	v_pk_mul_f32 v[10:11], v[46:47], v[50:51]
	v_pk_mul_f32 v[52:53], v[46:47], v[52:53]
	v_pk_mul_f32 v[50:51], v[24:25], v[10:11]
	s_waitcnt vmcnt(0)
	v_mov_b64_e32 v[10:11], v[180:181]
	v_mov_b64_e32 v[12:13], v[182:183]
	v_mov_b64_e32 v[14:15], v[184:185]
	v_mov_b64_e32 v[16:17], v[186:187]
	v_mov_b64_e32 v[18:19], v[188:189]
	v_mov_b64_e32 v[20:21], v[190:191]
	v_mov_b64_e32 v[58:59], v[192:193]
	v_mov_b64_e32 v[60:61], v[194:195]
	s_waitcnt lgkmcnt(0)
	v_mul_f32_e32 v45, v46, v56
	v_mul_f32_e32 v45, v0, v45
	v_pk_mul_f32 v[54:55], v[46:47], v[54:55]
	v_pk_mul_f32 v[52:53], v[26:27], v[52:53]
	v_pk_mul_f32 v[54:55], v[30:31], v[54:55]
	v_cndmask_b32_e64 v51, v51, -v51, s[40:41]
	v_cndmask_b32_e64 v50, v50, -v50, s[40:41]
	v_cndmask_b32_e64 v53, v53, -v53, s[40:41]
	v_cndmask_b32_e64 v52, v52, -v52, s[40:41]
	v_cndmask_b32_e64 v55, v55, -v55, s[40:41]
	v_cndmask_b32_e64 v54, v54, -v54, s[40:41]
	s_waitcnt vmcnt(3)
	v_mul_f32_e32 v8, v8, v12
	v_cndmask_b32_e64 v12, v45, -v45, s[40:41]
	s_waitcnt vmcnt(1)
	v_mul_f32_e32 v12, v12, v20
	v_mul_f32_e32 v20, v46, v57
	v_mul_f32_e32 v20, v48, v20
	v_cndmask_b32_e64 v47, v20, -v20, s[40:41]
	v_mov_b32_e32 v46, v9
	v_mov_b32_e32 v20, v13
	v_pk_mul_f32 v[20:21], v[46:47], v[20:21]
	s_waitcnt vmcnt(0)
	v_pk_mul_f32 v[50:51], v[58:59], v[50:51]
	v_pk_mul_f32 v[52:53], v[52:53], v[60:61]
	v_pk_mul_f32 v[18:19], v[54:55], v[18:19]
	v_mov_b32_e32 v9, v20
	v_mov_b32_e32 v13, v21
	v_pk_fma_f32 v[2:3], v[2:3], v[14:15], v[50:51]
	v_pk_fma_f32 v[4:5], v[4:5], v[16:17], v[52:53]
	v_pk_fma_f32 v[6:7], v[6:7], v[10:11], v[18:19]
	v_pk_add_f32 v[8:9], v[8:9], v[12:13]

.LBB0_1090:
	s_andn2_b64 vcc, exec, s[0:1]
	s_cbranch_vccnz .LBB0_1103
	v_cmp_lt_i32_e64 s[0:1], s43, v42
	v_cmp_gt_i32_e32 vcc, s80, v42
	s_and_saveexec_b64 s[4:5], vcc
	s_xor_b64 s[4:5], exec, s[4:5]
	v_and_b32_e32 v10, 0xff, v42
	s_or_saveexec_b64 s[4:5], s[4:5]
	v_mov_b32_e32 v44, v42
	s_xor_b64 exec, exec, s[4:5]
	v_add_u32_e32 v10, 0xffffe000, v42
	v_lshrrev_b32_e32 v11, 12, v10
	v_and_b32_e32 v10, 0xfff, v42
	v_mul_u32_u24_e32 v11, 0x1200, v11
	s_movk_i32 s6, 0x2200
	v_add3_u32 v44, v10, v11, s6
	s_or_b64 exec, exec, s[4:5]
	v_lshrrev_b32_e32 v196, 6, v10
	v_and_b32_e32 v197, 63, v10
	v_cndmask_b32_e64 v197, v197, v196, s[38:39]
	v_lshlrev_b32_e32 v196, 2, v115
	v_lshl_or_b32 v198, v197, 6, v196
	global_load_dwordx4 v[180:183], v198, s[10:11] offset:16
	global_load_dwordx4 v[184:187], v198, s[10:11]
	global_load_dwordx4 v[188:191], v198, s[12:13] offset:16
	global_load_dwordx4 v[192:195], v198, s[12:13]
	s_waitcnt lgkmcnt(1)
	v_pk_mul_f32 v[14:15], v[2:3], v[2:3]
	v_pk_mul_f32 v[12:13], v[4:5], v[4:5]
	v_add_f32_e32 v11, v14, v15
	v_add_f32_e32 v11, v12, v11
	s_waitcnt lgkmcnt(0)
	v_pk_mul_f32 v[18:19], v[6:7], v[6:7]
	v_add_f32_e32 v11, v13, v11
	v_add_f32_e32 v11, v18, v11
	v_pk_mul_f32 v[16:17], v[8:9], v[8:9]
	v_add_f32_e32 v11, v19, v11
	v_cmp_lt_i32_e32 vcc, v214, v215
	v_add_f32_e32 v11, v16, v11
	v_add_f32_e32 v11, v17, v11
	v_cndmask_b32_e32 v12, v213, v214, vcc
	v_lshlrev_b32_e32 v12, 2, v12
	ds_bpermute_b32 v12, v12, v11
	v_cmp_lt_i32_e32 vcc, v216, v215
	s_nor_b64 s[6:7], s[20:21], s[0:1]
	v_ashrrev_i32_e32 v43, 31, v42
	s_waitcnt lgkmcnt(0)
	v_add_f32_e32 v11, v11, v12
	v_cndmask_b32_e32 v12, v213, v216, vcc
	v_lshlrev_b32_e32 v12, 2, v12
	ds_bpermute_b32 v12, v12, v11
	v_cmp_lt_i32_e32 vcc, v217, v215
	s_waitcnt lgkmcnt(0)
	v_add_f32_e32 v11, v11, v12
	v_cndmask_b32_e32 v12, v213, v217, vcc
	v_lshlrev_b32_e32 v12, 2, v12
	ds_bpermute_b32 v12, v12, v11
	s_waitcnt lgkmcnt(0)
	v_add_f32_e32 v11, v11, v12
	v_fmamk_f32 v11, v11, 0x3c800000, v207
	v_mul_f32_e32 v12, 0x4b800000, v11
	v_cmp_gt_f32_e32 vcc, s42, v11
	s_nop 1
	v_cndmask_b32_e32 v11, v11, v12, vcc
	v_rsq_f32_e32 v11, v11
	s_nop 0
	v_mul_f32_e32 v12, 0x45800000, v11
	v_cndmask_b32_e32 v46, v11, v12, vcc
	v_pk_mul_f32 v[2:3], v[2:3], v[46:47] op_sel_hi:[1,0]
	v_pk_mul_f32 v[4:5], v[4:5], v[46:47] op_sel_hi:[1,0]
	v_pk_mul_f32 v[6:7], v[6:7], v[46:47] op_sel_hi:[1,0]
	v_pk_mul_f32 v[8:9], v[8:9], v[46:47] op_sel_hi:[1,0]
	s_waitcnt vmcnt(4)
	v_pk_mul_f32 v[2:3], v[32:33], v[2:3]
	v_pk_mul_f32 v[4:5], v[34:35], v[4:5]
	v_pk_mul_f32 v[6:7], v[36:37], v[6:7]
	v_pk_mul_f32 v[8:9], v[38:39], v[8:9]
	s_and_saveexec_b64 s[4:5], s[6:7]
	s_cbranch_execz .LBB0_1097
	v_readlane_b32 s6, v254, 13
	v_lshlrev_b64 v[12:13], 9, v[42:43]
	v_readlane_b32 s7, v254, 14
	s_nop 1
	v_lshl_add_u64 v[12:13], s[6:7], 0, v[12:13]
	v_lshl_add_u64 v[12:13], v[40:41], 2, v[12:13]
	v_add_co_u32_e32 v12, vcc, 0x5fff000, v12
	s_nop 1
	v_addc_co_u32_e32 v13, vcc, 0, v13, vcc
	global_store_dwordx4 v[12:13], v[2:5], off offset:2048
	global_store_dwordx4 v[12:13], v[6:9], off offset:2064
.LBB0_1097:
	s_or_b64 exec, exec, s[4:5]
	s_and_saveexec_b64 s[4:5], s[0:1]
	s_cbranch_execz .LBB0_1099
	ds_read_b128 v[32:35], v139
	ds_read_b128 v[36:39], v139 offset:16
	v_lshrrev_b32_e32 v11, 6, v10
	v_and_b32_e32 v10, 63, v10
	v_mov_b32_e32 v47, v46
	v_cndmask_b32_e64 v10, v10, v11, s[38:39]
	v_lshlrev_b32_e32 v11, 2, v115
	v_lshl_or_b32 v40, v10, 6, v11
	s_waitcnt lgkmcnt(1)
	v_pk_mul_f32 v[10:11], v[46:47], v[32:33]
	v_pk_mul_f32 v[32:33], v[46:47], v[34:35]
	v_pk_mul_f32 v[24:25], v[24:25], v[10:11]
	s_waitcnt vmcnt(0)
	v_mov_b64_e32 v[10:11], v[180:181]
	v_mov_b64_e32 v[12:13], v[182:183]
	v_mov_b64_e32 v[14:15], v[184:185]
	v_mov_b64_e32 v[16:17], v[186:187]
	v_mov_b64_e32 v[18:19], v[188:189]
	v_mov_b64_e32 v[20:21], v[190:191]
	v_mov_b64_e32 v[50:51], v[192:193]
	v_mov_b64_e32 v[52:53], v[194:195]
	v_pk_mul_f32 v[26:27], v[26:27], v[32:33]
	s_waitcnt lgkmcnt(0)
	v_pk_mul_f32 v[32:33], v[46:47], v[36:37]
	v_cndmask_b32_e64 v25, v25, -v25, s[40:41]
	v_pk_mul_f32 v[30:31], v[30:31], v[32:33]
	v_cndmask_b32_e64 v24, v24, -v24, s[40:41]
	v_cndmask_b32_e64 v31, v31, -v31, s[40:41]
	v_cndmask_b32_e64 v30, v30, -v30, s[40:41]
	v_cndmask_b32_e64 v27, v27, -v27, s[40:41]
	v_cndmask_b32_e64 v26, v26, -v26, s[40:41]
	s_waitcnt vmcnt(3)
	v_mul_f32_e32 v8, v8, v12
	s_waitcnt vmcnt(1)
	v_pk_mul_f32 v[18:19], v[30:31], v[18:19]
	v_mul_f32_e32 v30, v46, v38
	v_mul_f32_e32 v0, v0, v30
	v_cndmask_b32_e64 v0, v0, -v0, s[40:41]
	v_mul_f32_e32 v12, v0, v20
	v_mul_f32_e32 v0, v46, v39
	v_mul_f32_e32 v0, v48, v0
	v_cndmask_b32_e64 v31, v0, -v0, s[40:41]
	v_mov_b32_e32 v30, v9
	v_mov_b32_e32 v20, v13
	v_pk_mul_f32 v[20:21], v[30:31], v[20:21]
	s_waitcnt vmcnt(0)
	v_pk_mul_f32 v[24:25], v[50:51], v[24:25]
	v_pk_mul_f32 v[26:27], v[26:27], v[52:53]
	v_mov_b32_e32 v9, v20
	v_mov_b32_e32 v13, v21
	v_pk_fma_f32 v[2:3], v[2:3], v[14:15], v[24:25]
	v_pk_fma_f32 v[4:5], v[4:5], v[16:17], v[26:27]
	v_pk_fma_f32 v[6:7], v[6:7], v[10:11], v[18:19]
	v_pk_add_f32 v[8:9], v[8:9], v[12:13]
